# k-loop segment head after the barrier: first 4 MFMAs of the last group issued bare, DMA address block packed into the remaining 4 slots
# baseline (speedup 1.0000x reference)
; #define MFMA(a, b, c) __builtin_amdgcn_mfma_f32_32x32x16_bf16((a), (b), (c), 0, 0, 0)
;     ...
;     auto issue_at = [&](int mm0, int nn0, int kt, int buf) {
;       char* lb = L0 + buf * BUFB;
; #pragma unroll
;       for (int i = 0; i < 4; ++i) {
;         const int seg = wv * 4 + i, row = seg * 8 + gl_row;
;         const int c = (lane & 7) ^ ((row >> 1) & 7);
;         const u16* ap = (kt < g.split) ? g.a0 + (size_t)(mm0 + row) * g.ld0 + kt * g.ks0 : g.a1 + (size_t)(mm0 + row) * g.ld1 + (kt - g.split) * 64;
;         __builtin_amdgcn_global_load_lds((const unsigned*)(ap + c * 8), (__attribute__((address_space(3))) unsigned*)(lb + seg * 1024 + lane * 16), 16, 0, 0);
;       }
; #pragma unroll
;       for (int i = 0; i < BN / 64; ++i) {
;         const int seg = wv * (BN / 64) + i, row = seg * 8 + gl_row;
;         const int c = (lane & 7) ^ ((row >> 1) & 7);
;         __builtin_amdgcn_global_load_lds((const unsigned*)(g.W + (size_t)(nn0 + row) * g.K + kt * 64 + c * 8),
;                                          (__attribute__((address_space(3))) unsigned*)(lb + 256 * 128 + seg * 1024 + lane * 16), 16, 0, 0);
;       }
;     ...
;     auto compute2 = [&](int buf) {
;       const char* lb = L0 + buf * BUFB;
; #pragma unroll
;       for (int ks = 0; ks < 4; ++ks) {
;         const int c = ks * 2 + hh;
;         bf16x8 wf[2], xf[MI];
; #pragma unroll
;         for (int j = 0; j < 2; ++j) { const int r = wn * 64 + j * 32 + l32; wf[j] = *(const bf16x8*)(lb + 256 * 128 + r * 128 + ((c ^ ((r >> 1) & 7)) << 4)); }
; #pragma unroll
;         for (int i = 0; i < MI; ++i) { const int r = wm * (MI * 32) + i * 32 + l32; xf[i] = *(const bf16x8*)(lb + r * 128 + ((c ^ ((r >> 1) & 7)) << 4)); }
; #pragma unroll
;         for (int i = 0; i < MI; ++i) {
;           acc[i][0] = MFMA(wf[0], xf[i], acc[i][0]);
;           acc[i][1] = MFMA(wf[1], xf[i], acc[i][1]);
;         }
;       }
.Lgemm_g1_798:
	v_add_u32_e32 v0, s14, v173
	v_add_u32_e32 v176, v0, v171
	v_add_u32_e32 v0, v0, v170
	s_waitcnt lgkmcnt(3)
	v_mfma_f32_32x32x16_bf16 v[114:129], v[224:227], v[232:235], v[114:129]
	ds_read_b128 v[200:203], v176 offset:32768
	v_mfma_f32_32x32x16_bf16 v[98:113], v[228:231], v[232:235], v[98:113]
	ds_read_b128 v[204:207], v176 offset:36864
	s_waitcnt lgkmcnt(4)
	v_mfma_f32_32x32x16_bf16 v[82:97], v[224:227], v[240:243], v[82:97]
	ds_read_b128 v[208:211], v0
	v_mfma_f32_32x32x16_bf16 v[66:81], v[228:231], v[240:243], v[66:81]
	ds_read_b128 v[212:215], v0 offset:4096
	s_waitcnt lgkmcnt(5)
	v_mfma_f32_32x32x16_bf16 v[50:65], v[224:227], v[244:247], v[50:65]
	ds_read_b128 v[216:219], v0 offset:8192
	v_mfma_f32_32x32x16_bf16 v[34:49], v[228:231], v[244:247], v[34:49]
	ds_read_b128 v[220:223], v0 offset:12288
	s_waitcnt lgkmcnt(6)
	v_mfma_f32_32x32x16_bf16 v[18:33], v[224:227], v[248:251], v[18:33]
	v_mfma_f32_32x32x16_bf16 v[2:17], v[228:231], v[248:251], v[2:17]
	v_add_u32_e32 v0, s14, v172
	v_add_u32_e32 v176, v0, v171
	v_add_u32_e32 v0, v0, v170
	s_waitcnt lgkmcnt(3)
	v_mfma_f32_32x32x16_bf16 v[114:129], v[200:203], v[208:211], v[114:129]
	ds_read_b128 v[224:227], v176 offset:32768
	v_mfma_f32_32x32x16_bf16 v[98:113], v[204:207], v[208:211], v[98:113]
	ds_read_b128 v[228:231], v176 offset:36864
	s_waitcnt lgkmcnt(4)
	v_mfma_f32_32x32x16_bf16 v[82:97], v[200:203], v[212:215], v[82:97]
	ds_read_b128 v[232:235], v0
	v_mfma_f32_32x32x16_bf16 v[66:81], v[204:207], v[212:215], v[66:81]
	ds_read_b128 v[240:243], v0 offset:4096
	s_waitcnt lgkmcnt(5)
	v_mfma_f32_32x32x16_bf16 v[50:65], v[200:203], v[216:219], v[50:65]
	ds_read_b128 v[244:247], v0 offset:8192
	v_mfma_f32_32x32x16_bf16 v[34:49], v[204:207], v[216:219], v[34:49]
	ds_read_b128 v[248:251], v0 offset:12288
	s_waitcnt lgkmcnt(6)
	v_mfma_f32_32x32x16_bf16 v[18:33], v[200:203], v[220:223], v[18:33]
	v_mfma_f32_32x32x16_bf16 v[2:17], v[204:207], v[220:223], v[2:17]
	s_waitcnt vmcnt(0)
	s_waitcnt vmcnt(0) lgkmcnt(0)
	s_barrier
	s_cbranch_scc1 .Lgemm_exit_798
	s_and_b32 s14, s11, 0x10000
	s_xor_b32 s15, s14, 0x10000
	s_add_i32 s15, s15, 0
	s_add_i32 s14, s14, 0
	v_add_u32_e32 v0, s14, v175
	v_add_u32_e32 v176, v0, v171
	v_add_u32_e32 v0, v0, v170
	ds_read_b128 v[200:203], v176 offset:32768
	ds_read_b128 v[204:207], v176 offset:36864
	ds_read_b128 v[208:211], v0
	ds_read_b128 v[212:215], v0 offset:4096
	ds_read_b128 v[216:219], v0 offset:8192
	ds_read_b128 v[220:223], v0 offset:12288
	v_mfma_f32_32x32x16_bf16 v[114:129], v[224:227], v[232:235], v[114:129]
	v_mfma_f32_32x32x16_bf16 v[98:113], v[228:231], v[232:235], v[98:113]
	v_mfma_f32_32x32x16_bf16 v[82:97], v[224:227], v[240:243], v[82:97]
	v_mfma_f32_32x32x16_bf16 v[66:81], v[228:231], v[240:243], v[66:81]
	v_mfma_f32_32x32x16_bf16 v[50:65], v[224:227], v[244:247], v[50:65]
	s_add_i32 s64, s15, 0x8000
	s_add_i32 m0, s15, s60
	v_lshl_add_u64 v[176:177], v[152:153], 0, s[2:3]
	global_load_lds_dwordx4 v[176:177], off
	s_add_i32 m0, s15, s61
	v_lshl_add_u64 v[176:177], v[150:151], 0, s[2:3]
	global_load_lds_dwordx4 v[176:177], off
	v_mfma_f32_32x32x16_bf16 v[34:49], v[228:231], v[244:247], v[34:49]
	s_add_i32 m0, s15, s62
	v_lshl_add_u64 v[176:177], v[148:149], 0, s[2:3]
	global_load_lds_dwordx4 v[176:177], off
	s_add_i32 m0, s15, s63
	v_lshl_add_u64 v[176:177], v[146:147], 0, s[2:3]
	global_load_lds_dwordx4 v[176:177], off
	s_add_i32 m0, s64, s60
	v_mfma_f32_32x32x16_bf16 v[18:33], v[224:227], v[248:251], v[18:33]
	v_lshl_add_u64 v[176:177], v[144:145], 0, s[2:3]
	global_load_lds_dwordx4 v[176:177], off
	s_add_i32 m0, s64, s61
	v_lshl_add_u64 v[176:177], v[142:143], 0, s[2:3]
	global_load_lds_dwordx4 v[176:177], off
	s_add_i32 m0, s64, s62
	v_lshl_add_u64 v[176:177], v[140:141], 0, s[2:3]
	v_mfma_f32_32x32x16_bf16 v[2:17], v[228:231], v[248:251], v[2:17]
	global_load_lds_dwordx4 v[176:177], off
	s_add_i32 m0, s64, s63
	v_lshl_add_u64 v[176:177], v[138:139], 0, s[2:3]
	global_load_lds_dwordx4 v[176:177], off
	s_branch .Lgemm_rot_798

; #define MFMA(a, b, c) __builtin_amdgcn_mfma_f32_32x32x16_bf16((a), (b), (c), 0, 0, 0)
;     ...
;     auto issue_at = [&](int mm0, int nn0, int kt, int buf) {
;       char* lb = L0 + buf * BUFB;
; #pragma unroll
;       for (int i = 0; i < 4; ++i) {
;         const int seg = wv * 4 + i, row = seg * 8 + gl_row;
;         const int c = (lane & 7) ^ ((row >> 1) & 7);
;         const u16* ap = (kt < g.split) ? g.a0 + (size_t)(mm0 + row) * g.ld0 + kt * g.ks0 : g.a1 + (size_t)(mm0 + row) * g.ld1 + (kt - g.split) * 64;
;         __builtin_amdgcn_global_load_lds((const unsigned*)(ap + c * 8), (__attribute__((address_space(3))) unsigned*)(lb + seg * 1024 + lane * 16), 16, 0, 0);
;       }
; #pragma unroll
;       for (int i = 0; i < BN / 64; ++i) {
;         const int seg = wv * (BN / 64) + i, row = seg * 8 + gl_row;
;         const int c = (lane & 7) ^ ((row >> 1) & 7);
;         __builtin_amdgcn_global_load_lds((const unsigned*)(g.W + (size_t)(nn0 + row) * g.K + kt * 64 + c * 8),
;                                          (__attribute__((address_space(3))) unsigned*)(lb + 256 * 128 + seg * 1024 + lane * 16), 16, 0, 0);
;       }
;     ...
;     auto compute2 = [&](int buf) {
;       const char* lb = L0 + buf * BUFB;
; #pragma unroll
;       for (int ks = 0; ks < 4; ++ks) {
;         const int c = ks * 2 + hh;
;         bf16x8 wf[2], xf[MI];
; #pragma unroll
;         for (int j = 0; j < 2; ++j) { const int r = wn * 64 + j * 32 + l32; wf[j] = *(const bf16x8*)(lb + 256 * 128 + r * 128 + ((c ^ ((r >> 1) & 7)) << 4)); }
; #pragma unroll
;         for (int i = 0; i < MI; ++i) { const int r = wm * (MI * 32) + i * 32 + l32; xf[i] = *(const bf16x8*)(lb + r * 128 + ((c ^ ((r >> 1) & 7)) << 4)); }
; #pragma unroll
;         for (int i = 0; i < MI; ++i) {
;           acc[i][0] = MFMA(wf[0], xf[i], acc[i][0]);
;           acc[i][1] = MFMA(wf[1], xf[i], acc[i][1]);
;         }
;       }
.Lgemm_g1_1274:
	v_add_u32_e32 v233, s59, v199
	v_add_u32_e32 v230, v233, v175
	v_add_u32_e32 v234, v233, v174
	s_waitcnt lgkmcnt(3)
	v_mfma_f32_32x32x16_bf16 v[114:129], v[240:243], v[248:251], v[114:129]
	ds_read_b128 v[202:205], v230 offset:32768
	v_mfma_f32_32x32x16_bf16 v[98:113], v[244:247], v[248:251], v[98:113]
	ds_read_b128 v[206:209], v230 offset:36864
	s_waitcnt lgkmcnt(4)
	v_mfma_f32_32x32x16_bf16 v[82:97], v[240:243], v[214:217], v[82:97]
	ds_read_b128 v[210:213], v234
	v_mfma_f32_32x32x16_bf16 v[66:81], v[244:247], v[214:217], v[66:81]
	ds_read_b128 v[214:217], v234 offset:4096
	s_waitcnt lgkmcnt(5)
	v_mfma_f32_32x32x16_bf16 v[50:65], v[240:243], v[218:221], v[50:65]
	v_mfma_f32_32x32x16_bf16 v[34:49], v[244:247], v[218:221], v[34:49]
	ds_read_b128 v[218:221], v234 offset:8192
	s_waitcnt lgkmcnt(5)
	v_mfma_f32_32x32x16_bf16 v[18:33], v[240:243], v[222:225], v[18:33]
	v_mfma_f32_32x32x16_bf16 v[2:17], v[244:247], v[222:225], v[2:17]
	ds_read_b128 v[222:225], v234 offset:12288
	v_add_u32_e32 v233, s59, v176
	v_add_u32_e32 v230, v233, v175
	v_add_u32_e32 v234, v233, v174
	s_waitcnt lgkmcnt(3)
	v_mfma_f32_32x32x16_bf16 v[114:129], v[202:205], v[210:213], v[114:129]
	ds_read_b128 v[240:243], v230 offset:32768
	v_mfma_f32_32x32x16_bf16 v[98:113], v[206:209], v[210:213], v[98:113]
	ds_read_b128 v[244:247], v230 offset:36864
	s_waitcnt lgkmcnt(4)
	v_mfma_f32_32x32x16_bf16 v[82:97], v[202:205], v[214:217], v[82:97]
	ds_read_b128 v[248:251], v234
	v_mfma_f32_32x32x16_bf16 v[66:81], v[206:209], v[214:217], v[66:81]
	ds_read_b128 v[214:217], v234 offset:4096
	s_waitcnt lgkmcnt(5)
	v_mfma_f32_32x32x16_bf16 v[50:65], v[202:205], v[218:221], v[50:65]
	v_mfma_f32_32x32x16_bf16 v[34:49], v[206:209], v[218:221], v[34:49]
	ds_read_b128 v[218:221], v234 offset:8192
	s_waitcnt lgkmcnt(5)
	v_mfma_f32_32x32x16_bf16 v[18:33], v[202:205], v[222:225], v[18:33]
	v_mfma_f32_32x32x16_bf16 v[2:17], v[206:209], v[222:225], v[2:17]
	ds_read_b128 v[222:225], v234 offset:12288
	s_waitcnt vmcnt(0)
	s_waitcnt vmcnt(0) lgkmcnt(0)
	s_barrier
	s_cbranch_scc1 .Lgemm_exit_1274
	s_and_b32 s59, s56, 0x10000
	s_xor_b32 s60, s59, 0x10000
	s_add_i32 s57, s58, 1
	s_add_i32 s60, s60, 0
	s_cmp_lt_u32 s58, 21
	s_cselect_b64 vcc, -1, 0
	v_add_u32_e32 v233, s59, v201
	v_add_u32_e32 v230, v233, v175
	v_add_u32_e32 v234, v233, v174
	ds_read_b128 v[202:205], v230 offset:32768
	ds_read_b128 v[206:209], v230 offset:36864
	ds_read_b128 v[210:213], v234
	v_mfma_f32_32x32x16_bf16 v[114:129], v[240:243], v[248:251], v[114:129]
	v_mfma_f32_32x32x16_bf16 v[98:113], v[244:247], v[248:251], v[98:113]
	v_mfma_f32_32x32x16_bf16 v[82:97], v[240:243], v[214:217], v[82:97]
	v_mfma_f32_32x32x16_bf16 v[66:81], v[244:247], v[214:217], v[66:81]
	ds_read_b128 v[214:217], v234 offset:4096
	v_mfma_f32_32x32x16_bf16 v[50:65], v[240:243], v[218:221], v[50:65]
	s_add_i32 s66, s60, 0x8000
	v_lshl_add_u64 v[226:227], v[160:161], 0, s[2:3]
	v_lshl_add_u64 v[228:229], v[144:145], 0, s[2:3]
	v_cndmask_b32_e32 v227, v229, v227, vcc
	v_cndmask_b32_e32 v226, v228, v226, vcc
	v_lshl_add_u64 v[226:227], v[0:1], 1, v[226:227]
	s_add_i32 m0, s60, s62
	v_lshl_add_u64 v[228:229], v[142:143], 0, s[2:3]
	global_load_lds_dwordx4 v[226:227], off
	v_lshl_add_u64 v[226:227], v[158:159], 0, s[2:3]
	v_cndmask_b32_e32 v227, v229, v227, vcc
	v_mfma_f32_32x32x16_bf16 v[34:49], v[244:247], v[218:221], v[34:49]
	ds_read_b128 v[218:221], v234 offset:8192
	v_cndmask_b32_e32 v226, v228, v226, vcc
	v_lshl_add_u64 v[226:227], v[130:131], 1, v[226:227]
	s_add_i32 m0, s60, s63
	v_lshl_add_u64 v[228:229], v[140:141], 0, s[2:3]
	global_load_lds_dwordx4 v[226:227], off
	v_lshl_add_u64 v[226:227], v[156:157], 0, s[2:3]
	v_cndmask_b32_e32 v227, v229, v227, vcc
	v_cndmask_b32_e32 v226, v228, v226, vcc
	v_lshl_add_u64 v[226:227], v[132:133], 1, v[226:227]
	s_add_i32 m0, s60, s64
	v_lshl_add_u64 v[228:229], v[138:139], 0, s[2:3]
	v_mfma_f32_32x32x16_bf16 v[18:33], v[240:243], v[222:225], v[18:33]
	global_load_lds_dwordx4 v[226:227], off
	v_lshl_add_u64 v[226:227], v[154:155], 0, s[2:3]
	v_cndmask_b32_e32 v226, v228, v226, vcc
	v_cndmask_b32_e32 v227, v229, v227, vcc
	s_add_i32 m0, s60, s65
	v_lshl_add_u64 v[226:227], v[134:135], 1, v[226:227]
	global_load_lds_dwordx4 v[226:227], off
	s_add_i32 m0, s66, s62
	v_lshl_add_u64 v[226:227], v[146:147], 0, s[2:3]
	global_load_lds_dwordx4 v[226:227], off
	s_add_i32 m0, s66, s63
	v_mfma_f32_32x32x16_bf16 v[2:17], v[244:247], v[222:225], v[2:17]
	ds_read_b128 v[222:225], v234 offset:12288
	v_lshl_add_u64 v[226:227], v[148:149], 0, s[2:3]
	global_load_lds_dwordx4 v[226:227], off
	s_add_i32 m0, s66, s64
	v_lshl_add_u64 v[226:227], v[150:151], 0, s[2:3]
	global_load_lds_dwordx4 v[226:227], off
	v_lshl_add_u64 v[226:227], v[152:153], 0, s[2:3]
	s_add_i32 m0, s66, s65
	s_add_i32 s58, s59, 0
	global_load_lds_dwordx4 v[226:227], off
	s_branch .Lgemm_rot_1274

; #define MFMA(a, b, c) __builtin_amdgcn_mfma_f32_32x32x16_bf16((a), (b), (c), 0, 0, 0)
;     ...
;     auto issue_at = [&](int mm0, int nn0, int kt, int buf) {
;       char* lb = L0 + buf * BUFB;
; #pragma unroll
;       for (int i = 0; i < 4; ++i) {
;         const int seg = wv * 4 + i, row = seg * 8 + gl_row;
;         const int c = (lane & 7) ^ ((row >> 1) & 7);
;         const u16* ap = (kt < g.split) ? g.a0 + (size_t)(mm0 + row) * g.ld0 + kt * g.ks0 : g.a1 + (size_t)(mm0 + row) * g.ld1 + (kt - g.split) * 64;
;         __builtin_amdgcn_global_load_lds((const unsigned*)(ap + c * 8), (__attribute__((address_space(3))) unsigned*)(lb + seg * 1024 + lane * 16), 16, 0, 0);
;       }
; #pragma unroll
;       for (int i = 0; i < BN / 64; ++i) {
;         const int seg = wv * (BN / 64) + i, row = seg * 8 + gl_row;
;         const int c = (lane & 7) ^ ((row >> 1) & 7);
;         __builtin_amdgcn_global_load_lds((const unsigned*)(g.W + (size_t)(nn0 + row) * g.K + kt * 64 + c * 8),
;                                          (__attribute__((address_space(3))) unsigned*)(lb + 256 * 128 + seg * 1024 + lane * 16), 16, 0, 0);
;       }
;     ...
;     auto compute2 = [&](int buf) {
;       const char* lb = L0 + buf * BUFB;
; #pragma unroll
;       for (int ks = 0; ks < 4; ++ks) {
;         const int c = ks * 2 + hh;
;         bf16x8 wf[2], xf[MI];
; #pragma unroll
;         for (int j = 0; j < 2; ++j) { const int r = wn * 64 + j * 32 + l32; wf[j] = *(const bf16x8*)(lb + 256 * 128 + r * 128 + ((c ^ ((r >> 1) & 7)) << 4)); }
; #pragma unroll
;         for (int i = 0; i < MI; ++i) { const int r = wm * (MI * 32) + i * 32 + l32; xf[i] = *(const bf16x8*)(lb + r * 128 + ((c ^ ((r >> 1) & 7)) << 4)); }
; #pragma unroll
;         for (int i = 0; i < MI; ++i) {
;           acc[i][0] = MFMA(wf[0], xf[i], acc[i][0]);
;           acc[i][1] = MFMA(wf[1], xf[i], acc[i][1]);
;         }
;       }
.Lgemm_g1_1371:
	v_add_u32_e32 v0, s17, v172
	v_add_u32_e32 v175, v0, v170
	v_add_u32_e32 v0, v0, v169
	s_waitcnt lgkmcnt(3)
	v_mfma_f32_32x32x16_bf16 v[114:129], v[224:227], v[232:235], v[114:129]
	ds_read_b128 v[200:203], v175 offset:32768
	v_mfma_f32_32x32x16_bf16 v[98:113], v[228:231], v[232:235], v[98:113]
	ds_read_b128 v[204:207], v175 offset:36864
	s_waitcnt lgkmcnt(4)
	v_mfma_f32_32x32x16_bf16 v[82:97], v[224:227], v[240:243], v[82:97]
	ds_read_b128 v[208:211], v0
	v_mfma_f32_32x32x16_bf16 v[66:81], v[228:231], v[240:243], v[66:81]
	ds_read_b128 v[212:215], v0 offset:4096
	s_waitcnt lgkmcnt(5)
	v_mfma_f32_32x32x16_bf16 v[50:65], v[224:227], v[244:247], v[50:65]
	ds_read_b128 v[216:219], v0 offset:8192
	v_mfma_f32_32x32x16_bf16 v[34:49], v[228:231], v[244:247], v[34:49]
	ds_read_b128 v[220:223], v0 offset:12288
	s_waitcnt lgkmcnt(6)
	v_mfma_f32_32x32x16_bf16 v[18:33], v[224:227], v[248:251], v[18:33]
	v_mfma_f32_32x32x16_bf16 v[2:17], v[228:231], v[248:251], v[2:17]
	v_add_u32_e32 v0, s17, v171
	v_add_u32_e32 v175, v0, v170
	v_add_u32_e32 v0, v0, v169
	s_waitcnt lgkmcnt(3)
	v_mfma_f32_32x32x16_bf16 v[114:129], v[200:203], v[208:211], v[114:129]
	ds_read_b128 v[224:227], v175 offset:32768
	v_mfma_f32_32x32x16_bf16 v[98:113], v[204:207], v[208:211], v[98:113]
	ds_read_b128 v[228:231], v175 offset:36864
	s_waitcnt lgkmcnt(4)
	v_mfma_f32_32x32x16_bf16 v[82:97], v[200:203], v[212:215], v[82:97]
	ds_read_b128 v[232:235], v0
	v_mfma_f32_32x32x16_bf16 v[66:81], v[204:207], v[212:215], v[66:81]
	ds_read_b128 v[240:243], v0 offset:4096
	s_waitcnt lgkmcnt(5)
	v_mfma_f32_32x32x16_bf16 v[50:65], v[200:203], v[216:219], v[50:65]
	ds_read_b128 v[244:247], v0 offset:8192
	v_mfma_f32_32x32x16_bf16 v[34:49], v[204:207], v[216:219], v[34:49]
	ds_read_b128 v[248:251], v0 offset:12288
	s_waitcnt lgkmcnt(6)
	v_mfma_f32_32x32x16_bf16 v[18:33], v[200:203], v[220:223], v[18:33]
	v_mfma_f32_32x32x16_bf16 v[2:17], v[204:207], v[220:223], v[2:17]
	s_waitcnt vmcnt(0)
	s_waitcnt vmcnt(0) lgkmcnt(0)
	s_barrier
	s_cbranch_scc1 .Lgemm_exit_1371
	s_and_b32 s17, s16, 0x10000
	s_xor_b32 s43, s17, 0x10000
	s_add_i32 s43, s43, 0
	s_add_i32 s17, s17, 0
	v_add_u32_e32 v0, s17, v174
	v_add_u32_e32 v175, v0, v170
	v_add_u32_e32 v0, v0, v169
	ds_read_b128 v[200:203], v175 offset:32768
	ds_read_b128 v[204:207], v175 offset:36864
	ds_read_b128 v[208:211], v0
	ds_read_b128 v[212:215], v0 offset:4096
	ds_read_b128 v[216:219], v0 offset:8192
	ds_read_b128 v[220:223], v0 offset:12288
	v_mfma_f32_32x32x16_bf16 v[114:129], v[224:227], v[232:235], v[114:129]
	v_mfma_f32_32x32x16_bf16 v[98:113], v[228:231], v[232:235], v[98:113]
	v_mfma_f32_32x32x16_bf16 v[82:97], v[224:227], v[240:243], v[82:97]
	v_mfma_f32_32x32x16_bf16 v[66:81], v[228:231], v[240:243], v[66:81]
	v_mfma_f32_32x32x16_bf16 v[50:65], v[224:227], v[244:247], v[50:65]
	s_add_i32 s64, s43, 0x8000
	s_add_i32 m0, s43, s60
	v_lshl_add_u64 v[176:177], v[152:153], 0, s[10:11]
	global_load_lds_dwordx4 v[176:177], off
	s_add_i32 m0, s43, s61
	v_lshl_add_u64 v[176:177], v[150:151], 0, s[10:11]
	global_load_lds_dwordx4 v[176:177], off
	v_mfma_f32_32x32x16_bf16 v[34:49], v[228:231], v[244:247], v[34:49]
	s_add_i32 m0, s43, s62
	v_lshl_add_u64 v[176:177], v[148:149], 0, s[10:11]
	global_load_lds_dwordx4 v[176:177], off
	s_add_i32 m0, s43, s63
	v_lshl_add_u64 v[176:177], v[146:147], 0, s[10:11]
	global_load_lds_dwordx4 v[176:177], off
	s_add_i32 m0, s64, s60
	v_mfma_f32_32x32x16_bf16 v[18:33], v[224:227], v[248:251], v[18:33]
	v_lshl_add_u64 v[176:177], v[144:145], 0, s[10:11]
	global_load_lds_dwordx4 v[176:177], off
	s_add_i32 m0, s64, s61
	v_lshl_add_u64 v[176:177], v[142:143], 0, s[10:11]
	global_load_lds_dwordx4 v[176:177], off
	s_add_i32 m0, s64, s62
	v_lshl_add_u64 v[176:177], v[140:141], 0, s[10:11]
	v_mfma_f32_32x32x16_bf16 v[2:17], v[228:231], v[248:251], v[2:17]
	global_load_lds_dwordx4 v[176:177], off
	s_add_i32 m0, s64, s63
	v_lshl_add_u64 v[176:177], v[138:139], 0, s[10:11]
	global_load_lds_dwordx4 v[176:177], off
	s_branch .Lgemm_rot_1371
